# v156 plus three individually neutral changes: ph3 with all loads up front, GEMM prologue reorder, CONV-GEMM column remap
# baseline (speedup 1.0000x reference)
.LBB0_121:
	s_waitcnt vmcnt(8)
	s_barrier
	s_lshl_b32 s11, s11, 5
	v_lshrrev_b32_e32 v2, 1, v15
	v_and_b32_e32 v2, 24, v2
	s_and_b32 s34, s11, 0x60
	v_and_b32_e32 v1, 15, v15
	v_lshlrev_b32_e32 v3, 1, v2
	v_or_b32_e32 v172, s34, v2
	v_rcp_iflag_f32_e32 v2, v14
	v_lshlrev_b32_e32 v241, 2, v1
	s_lshr_b32 s83, s10, 6
	v_lshl_or_b32 v3, v1, 6, v3
	v_and_b32_e32 v4, 32, v241
	s_mov_b32 s100, 0x14000
	s_mov_b32 s11, 7
	s_cmp_eq_u32 s81, 0
	s_cbranch_scc1 .Lfl_remap
	s_cmp_eq_u32 s81, 3
	s_cbranch_scc1 .Lfl_remap
	s_cmp_eq_u32 s81, 4
	s_cbranch_scc1 .Lfl_remap
	s_branch .Lfl_noremap
